# grid barrier: first block to arrive in each XCD issues an early asynchronous L2 writeback
# baseline (speedup 1.0000x reference)
; DI unsigned xb_ld(unsigned* p)              { return __hip_atomic_load(p, __ATOMIC_RELAXED, __HIP_MEMORY_SCOPE_AGENT); }
; DI unsigned xb_add(unsigned* p, unsigned v) { return __hip_atomic_fetch_add(p, v, __ATOMIC_RELAXED, __HIP_MEMORY_SCOPE_AGENT); }
; #define XB_SPIN(cond, bar) do { unsigned _sp = 0; while (cond) { __builtin_amdgcn_s_sleep(1); \
;     if ((++_sp & 255u) == 0u) { if (xb_ld(&(bar)[XB_TMO])) break; if (_sp > XB_SPIN_CAP) { atomicAdd(&(bar)[XB_TMO], 1u); break; } } } } while (0)
; DI void xcd_barrier(const XcdBarrier& b) {
;     ...
;     unsigned nloc = b.st[0], nx = b.st[1];
;     if (nloc == 0u) { xcd_barrier_complete(bar, b.x, nloc, nx); b.st[0] = nloc; b.st[1] = nx; }
;     const unsigned old = xb_add(&bar[XB_XSUB(b.x)], 1u);
;     const unsigned gen = old / nloc;
;     if (old + 1u == (gen + 1u) * nloc) {
;       __builtin_amdgcn_fence(__ATOMIC_RELEASE, "agent");
;       asm volatile("s_waitcnt vmcnt(0)" ::: "memory");
;       const unsigned og = xb_add(&bar[XB_TOP], 1u);
;       const unsigned tg = og / nx;
;       if (og + 1u == (tg + 1u) * nx) xb_add(&bar[XB_TOPGEN], 1u);
;       else XB_SPIN(xb_ld(&bar[XB_TOPGEN]) == tg, bar);
;       __builtin_amdgcn_fence(__ATOMIC_ACQUIRE, "agent");
;       xb_add(&bar[XB_XGEN(b.x)], 1u);
;       asm volatile("s_waitcnt vmcnt(0)" ::: "memory");
;     } else {
;       XB_SPIN(xb_ld(&bar[XB_XGEN(b.x)]) == gen, bar);
.LBB0_2080:
	s_or_b64 exec, exec, s[30:31]
	v_cvt_f32_u32_e32 v5, v3
	s_waitcnt vmcnt(0)
	v_readfirstlane_b32 s28, v4
	v_sub_u32_e32 v4, 0, v3
	v_rcp_iflag_f32_e32 v5, v5
	v_add_u32_e32 v6, s28, v0
	v_mul_f32_e32 v5, 0x4f7ffffe, v5
	v_cvt_u32_f32_e32 v5, v5
	v_mul_lo_u32 v0, v4, v5
	v_mul_hi_u32 v0, v5, v0
	v_add_u32_e32 v0, v5, v0
	v_mul_hi_u32 v0, v6, v0
	v_mul_lo_u32 v4, v0, v3
	v_sub_u32_e32 v4, v6, v4
	v_add_u32_e32 v5, 1, v0
	v_cmp_ge_u32_e32 vcc, v4, v3
	s_nop 1
	v_cndmask_b32_e32 v0, v0, v5, vcc
	v_sub_u32_e32 v5, v4, v3
	v_cndmask_b32_e32 v4, v4, v5, vcc
	v_add_u32_e32 v5, 1, v0
	v_cmp_ge_u32_e32 vcc, v4, v3
	v_add_u32_e32 v4, 1, v6
	s_nop 0
	v_cndmask_b32_e32 v0, v0, v5, vcc
	v_mul_lo_u32 v5, v3, v0
	v_add_u32_e32 v3, v5, v3
	v_cmp_ne_u32_e32 vcc, v4, v3
	s_and_saveexec_b64 s[30:31], vcc
	s_xor_b64 s[30:31], exec, s[30:31]
	s_cbranch_execz .LBB0_2094
	v_cmp_ne_u32_e32 vcc, v6, v5
	s_cbranch_vccnz .Lbar_noflush
	buffer_wbl2 sc1
.Lbar_noflush:
	v_readlane_b32 s4, v254, 60
	v_readlane_b32 s5, v254, 61
	s_waitcnt lgkmcnt(0)
	v_mad_u32_u24 v7, v0, v2, v2
	s_nop 2
	global_load_dword v2, v1, s[4:5] sc1
	s_waitcnt vmcnt(0)
	v_cmp_lt_u32_e32 vcc, v2, v7
	s_and_saveexec_b64 s[40:41], vcc
	s_cbranch_execz .LBB0_2093
	s_mov_b32 s28, 1
	s_mov_b64 s[42:43], 0
	s_branch .LBB0_2084
